# al1 + nt hint on the in-proj GEMM epilogue P stores (16 per tile)
# baseline (speedup 1.0000x reference)
.LBB0_277:
	v_lshl_or_b32 v140, s39, 8, v146
	v_lshl_add_u32 v150, s40, 8, v142
	v_ashrrev_i32_e32 v141, 31, v140
	v_mov_b64_e32 v[138:139], s[8:9]
	v_mad_i64_i32 v[148:149], s[20:21], v150, s3, v[138:139]
	v_lshlrev_b64 v[140:141], 1, v[140:141]
	v_lshl_add_u64 v[148:149], v[148:149], 0, v[140:141]
	v_cvt_pk_bf16_f32 v124, v124, v125
	v_cvt_pk_bf16_f32 v125, v126, v127
	v_cvt_pk_bf16_f32 v126, v120, v121
	v_cvt_pk_bf16_f32 v127, v122, v123
	global_store_dwordx4 v[148:149], v[124:127], off nt
	v_cvt_pk_bf16_f32 v112, v112, v113
	v_cvt_pk_bf16_f32 v113, v114, v115
	v_cvt_pk_bf16_f32 v114, v104, v105
	v_or_b32_e32 v104, 16, v150
	v_mad_i64_i32 v[104:105], s[20:21], v104, s3, v[138:139]
	v_cvt_pk_bf16_f32 v115, v106, v107
	global_store_dwordx4 v[148:149], v[112:115], off offset:256 nt
	s_andn2_b64 vcc, exec, s[4:5]
	s_mov_b64 s[4:5], -1
	v_lshl_add_u64 v[112:113], v[104:105], 0, v[140:141]
	v_cvt_pk_bf16_f32 v104, v116, v117
	v_cvt_pk_bf16_f32 v105, v118, v119
	v_cvt_pk_bf16_f32 v106, v108, v109
	v_cvt_pk_bf16_f32 v107, v110, v111
	global_store_dwordx4 v[112:113], v[104:107], off nt
	v_cvt_pk_bf16_f32 v96, v96, v97
	v_cvt_pk_bf16_f32 v97, v98, v99
	v_cvt_pk_bf16_f32 v98, v88, v89
	v_or_b32_e32 v88, 32, v150
	v_mad_i64_i32 v[88:89], s[20:21], v88, s3, v[138:139]
	v_cvt_pk_bf16_f32 v99, v90, v91
	global_store_dwordx4 v[112:113], v[96:99], off offset:256 nt
	s_nop 1
	v_lshl_add_u64 v[96:97], v[88:89], 0, v[140:141]
	v_cvt_pk_bf16_f32 v88, v100, v101
	v_cvt_pk_bf16_f32 v89, v102, v103
	v_cvt_pk_bf16_f32 v90, v92, v93
	v_cvt_pk_bf16_f32 v91, v94, v95
	global_store_dwordx4 v[96:97], v[88:91], off nt
	v_cvt_pk_bf16_f32 v80, v80, v81
	v_cvt_pk_bf16_f32 v81, v82, v83
	v_cvt_pk_bf16_f32 v82, v72, v73
	v_or_b32_e32 v72, 48, v150
	v_mad_i64_i32 v[72:73], s[20:21], v72, s3, v[138:139]
	v_cvt_pk_bf16_f32 v83, v74, v75
	global_store_dwordx4 v[96:97], v[80:83], off offset:256 nt
	s_nop 1
	v_lshl_add_u64 v[80:81], v[72:73], 0, v[140:141]
	v_cvt_pk_bf16_f32 v72, v84, v85
	v_cvt_pk_bf16_f32 v73, v86, v87
	v_cvt_pk_bf16_f32 v74, v76, v77
	v_cvt_pk_bf16_f32 v75, v78, v79
	global_store_dwordx4 v[80:81], v[72:75], off nt
	v_cvt_pk_bf16_f32 v68, v68, v69
	v_cvt_pk_bf16_f32 v69, v70, v71
	v_cvt_pk_bf16_f32 v70, v64, v65
	v_add_u32_e32 v64, 0x80, v150
	v_mad_i64_i32 v[64:65], s[20:21], v64, s3, v[138:139]
	v_lshl_add_u64 v[64:65], v[64:65], 0, v[140:141]
	v_cvt_pk_bf16_f32 v71, v66, v67
	global_store_dwordx4 v[80:81], v[68:71], off offset:256 nt
	v_cvt_pk_bf16_f32 v60, v60, v61
	v_cvt_pk_bf16_f32 v61, v62, v63
	v_cvt_pk_bf16_f32 v62, v56, v57
	v_cvt_pk_bf16_f32 v63, v58, v59
	global_store_dwordx4 v[64:65], v[60:63], off nt
	v_cvt_pk_bf16_f32 v48, v48, v49
	v_cvt_pk_bf16_f32 v49, v50, v51
	v_cvt_pk_bf16_f32 v50, v40, v41
	v_add_u32_e32 v40, 0x90, v150
	v_mad_i64_i32 v[40:41], s[20:21], v40, s3, v[138:139]
	v_cvt_pk_bf16_f32 v51, v42, v43
	global_store_dwordx4 v[64:65], v[48:51], off offset:256 nt
	s_nop 1
	v_lshl_add_u64 v[48:49], v[40:41], 0, v[140:141]
	v_cvt_pk_bf16_f32 v40, v52, v53
	v_cvt_pk_bf16_f32 v41, v54, v55
	v_cvt_pk_bf16_f32 v42, v44, v45
	v_cvt_pk_bf16_f32 v43, v46, v47
	global_store_dwordx4 v[48:49], v[40:43], off nt
	v_cvt_pk_bf16_f32 v32, v32, v33
	v_cvt_pk_bf16_f32 v33, v34, v35
	v_cvt_pk_bf16_f32 v34, v24, v25
	v_add_u32_e32 v24, 0xa0, v150
	v_mad_i64_i32 v[24:25], s[20:21], v24, s3, v[138:139]
	v_cvt_pk_bf16_f32 v35, v26, v27
	global_store_dwordx4 v[48:49], v[32:35], off offset:256 nt
	s_nop 1
	v_lshl_add_u64 v[32:33], v[24:25], 0, v[140:141]
	v_cvt_pk_bf16_f32 v24, v36, v37
	v_cvt_pk_bf16_f32 v25, v38, v39
	v_cvt_pk_bf16_f32 v26, v28, v29
	v_cvt_pk_bf16_f32 v27, v30, v31
	global_store_dwordx4 v[32:33], v[24:27], off nt
	v_cvt_pk_bf16_f32 v16, v16, v17
	v_cvt_pk_bf16_f32 v17, v18, v19
	v_cvt_pk_bf16_f32 v18, v8, v9
	v_add_u32_e32 v8, 0xb0, v150
	v_mad_i64_i32 v[8:9], s[20:21], v8, s3, v[138:139]
	v_cvt_pk_bf16_f32 v19, v10, v11
	global_store_dwordx4 v[32:33], v[16:19], off offset:256 nt
	s_nop 1
	v_lshl_add_u64 v[16:17], v[8:9], 0, v[140:141]
	v_cvt_pk_bf16_f32 v8, v20, v21
	v_cvt_pk_bf16_f32 v9, v22, v23
	v_cvt_pk_bf16_f32 v10, v12, v13
	v_cvt_pk_bf16_f32 v11, v14, v15
	global_store_dwordx4 v[16:17], v[8:11], off nt
	v_cvt_pk_bf16_f32 v4, v4, v5
	v_cvt_pk_bf16_f32 v5, v6, v7
	v_cvt_pk_bf16_f32 v6, v0, v1
	v_cvt_pk_bf16_f32 v7, v2, v3
	global_store_dwordx4 v[16:17], v[4:7], off offset:256 nt
	s_cbranch_vccnz .LBB0_266
	s_andn2_b64 vcc, exec, s[6:7]
	s_cbranch_vccnz .LBB0_265
	s_barrier
	s_branch .LBB0_265
